# G1 unit order: column-tile permutation tables re-balanced (no 5-unit workgroup gets 3 HGRN tiles); plus LN row-loop prefetch
# speedup vs baseline: 1.0058x; 1.0038x over previous
.LBB0_313:
	s_and_b64 vcc, exec, s[0:1]
	s_cbranch_vccz .LBB0_422
	s_cmpk_lt_i32 s2, 0x420
	v_mov_b32_e32 v8, v209
	s_mov_b32 s4, s81
	s_cselect_b64 s[0:1], -1, 0
	s_cmpk_gt_i32 s2, 0x41f
	s_cbranch_scc1 .LBB0_316
	s_ashr_i32 s5, s2, 31
	s_lshr_b32 s5, s5, 29
	s_add_i32 s5, s2, s5
	s_ashr_i32 s6, s5, 3
	s_and_b32 s5, s5, -8
	s_sub_i32 s5, s2, s5
	s_cmp_lt_i32 s5, 0
	s_movk_i32 s7, 0x85
	s_cselect_b32 s7, s7, 0x84
	s_mul_i32 s5, s5, s7
	s_add_i32 s5, s5, s6
	s_mul_hi_i32 s6, s5, 0x2e8ba2e9
	s_lshr_b32 s7, s6, 31
	s_ashr_i32 s6, s6, 5
	s_add_i32 s6, s6, s7
	s_lshl_b32 s7, s6, 3
	s_mulk_i32 s6, 0xb0
	s_sub_i32 s5, s5, s6
	s_bfe_u32 s6, s5, 0x3001c
	s_add_i32 s6, s5, s6
	s_sext_i32_i16 s8, s6
	s_and_b32 s6, s6, 0xfff8
	s_sub_i32 s6, s5, s6
	s_ashr_i32 s8, s8, 3
	s_sext_i32_i16 s6, s6
	s_add_i32 s38, s7, s6
	s_mul_i32 s8, s8, 5
	s_cmpk_lt_i32 s5, 0x60
	s_sext_i32_i16 s5, s8
	s_cselect_b64 s[6:7], -1, 0
	s_sub_i32 s8, s5, 60
	s_cmpk_eq_i32 s57, 0xd8
	s_mov_b32 s9, 0x5074a873
	s_mov_b32 s10, 0x251a3
	s_mov_b32 s11, 0x96c0bdd0
	s_mov_b32 s12, 0x292a201
	s_cselect_b32 s9, s9, 0x98f3aa8b
	s_cselect_b32 s10, s10, 0x7099
	s_cselect_b32 s11, s11, 0xab2410a1
	s_cselect_b32 s12, s12, 0x24516b
	s_and_b64 s[6:7], s[6:7], exec
	s_cselect_b32 s5, s5, s8
	s_cselect_b32 s7, s12, s10
	s_cselect_b32 s6, s11, s9
	s_lshr_b64 s[6:7], s[6:7], s5
	s_and_b32 s58, s6, 31

.LBB0_319:
	v_readlane_b32 s20, v254, 19
	v_readlane_b32 s21, v254, 20
	s_add_u32 s48, s20, 0x39a00000
	s_addc_u32 s49, s21, 0
	s_add_u32 s78, s20, 0x3e200000
	s_addc_u32 s79, s21, 0
	s_add_u32 s82, s20, 0x3fa00000
	s_addc_u32 s83, s21, 0
	s_add_u32 s86, s20, 0x41200000
	s_addc_u32 s87, s21, 0
	s_add_u32 s90, s20, 0x42a00000
	s_addc_u32 s91, s21, 0
	s_add_u32 s94, s20, 0x44200000
	s_addc_u32 s95, s21, 0
	s_add_u32 s6, s20, 0x28c00000
	s_addc_u32 s7, s21, 0
	v_writelane_b32 v254, s6, 29
	v_readlane_b32 s16, v253, 63
	s_lshl_b32 s8, s65, 10
	v_writelane_b32 v254, s7, 30
	v_lshl_add_u64 v[6:7], v[6:7], 0, s[96:97]
	v_readlane_b32 s17, v254, 0
	s_mov_b32 s1, s17
	v_readlane_b32 s18, v254, 1
	v_readlane_b32 s19, v254, 2
	s_mov_b32 s9, s17
	v_writelane_b32 v253, s0, 63
	s_lshl_b64 s[6:7], s[8:9], 2
	s_waitcnt vmcnt(2)
	s_barrier
	v_writelane_b32 v254, s1, 0
	v_writelane_b32 v254, s2, 1
	v_writelane_b32 v254, s3, 2
	s_add_u32 s1, s20, s6
	s_addc_u32 s5, s21, s7
	s_add_u32 s6, s1, 0x200000
	s_addc_u32 s7, s5, 0
	s_and_b32 s5, s4, 3
	s_add_i32 m0, s59, 0x18000
	v_writelane_b32 v254, s6, 31
	s_lshl_b32 s11, s0, 6
	s_lshl_b32 s15, s5, 5
	global_load_lds_dwordx4 v[6:7], off
	v_lshl_add_u64 v[4:5], v[4:5], 0, s[96:97]
	s_add_i32 m0, s59, 0x1a000
	s_add_i32 s12, s59, 0x8000
	s_add_i32 s13, s59, 0xa000
	v_writelane_b32 v254, s7, 32
	global_load_lds_dwordx4 v[4:5], off
	v_lshl_add_u64 v[0:1], v[0:1], 0, s[96:97]
	s_mov_b32 m0, s12
	s_add_u32 s6, s24, 0x80080
	global_load_lds_dwordx4 v[0:1], off
	v_lshl_add_u64 v[0:1], v[2:3], 0, s[96:97]
	s_mov_b32 m0, s13
	s_addc_u32 s7, s25, 0
	global_load_lds_dwordx4 v[0:1], off
	s_add_i32 m0, s59, 0x1c000
	v_lshl_add_u64 v[0:1], s[6:7], 0, v[174:175]
	global_load_lds_dwordx4 v[0:1], off
	v_lshl_add_u64 v[0:1], s[6:7], 0, v[176:177]
	s_add_i32 m0, s59, 0x1e000
	s_cmp_lt_u32 s4, 4
	global_load_lds_dwordx4 v[0:1], off
	v_and_b32_e32 v1, 0xfffffc00, v15
	v_lshl_add_u32 v2, s0, 13, v1
	v_lshl_add_u32 v1, s5, 12, v1
	s_cselect_b64 s[0:1], -1, 0
	s_lshl_b32 s5, s5, 4
	s_mov_b32 s35, s5
	s_or_b32 s5, s5, s15
	s_and_b32 s5, s5, 0x50
	v_writelane_b32 v254, s5, 33
	s_bfe_u32 s5, s4, 0x10001
	v_writelane_b32 v254, s5, 35
	s_and_b32 s4, s4, 1
	v_writelane_b32 v254, s4, 36
	s_and_b32 s4, s15, 32
	s_ashr_i32 s33, s57, 31
	s_ashr_i32 s84, s2, 31
	v_writelane_b32 v254, s4, 37
	s_cmpk_eq_i32 s57, 0xd8
	s_mov_b32 s4, 0x251a3
	s_cselect_b32 s4, s4, 0x7099
	v_writelane_b32 v254, s4, 38
	s_mov_b32 s4, 0x5074a873
	s_cselect_b32 s4, s4, 0x98f3aa8b
	v_writelane_b32 v254, s4, 39
	s_mov_b32 s4, 0x292a201
	v_and_b32_e32 v65, 15, v8
	v_and_b32_e32 v0, 48, v8
	v_lshlrev_b32_e32 v3, 2, v8
	s_cselect_b32 s4, s4, 0x24516b
	v_lshl_or_b32 v0, v65, 6, v0
	v_and_b32_e32 v3, 32, v3
	v_writelane_b32 v254, s4, 40
	s_mov_b32 s4, 0x96c0bdd0
	v_bitop3_b32 v2, v0, v2, v3 bitop3:0xde
	v_bitop3_b32 v201, v0, v1, v3 bitop3:0xde
	s_cselect_b32 s4, s4, 0xab2410a1
	v_lshlrev_b32_e32 v0, 15, v9
	v_writelane_b32 v254, s4, 41
	s_add_u32 s4, s20, 0x3ee00000
	v_and_b32_e32 v0, 0xffff0000, v0
	s_addc_u32 s5, s21, 0
	v_lshl_add_u32 v0, v10, 12, v0
	v_and_b32_e32 v1, 1, v9
	s_add_u32 s6, s20, 0x40600000
	v_lshl_or_b32 v0, v1, 6, v0
	s_addc_u32 s7, s21, 0
	v_lshl_add_u32 v178, v11, 1, v0
	v_lshlrev_b32_e32 v0, 15, v12
	s_add_u32 s8, s20, 0x44380000
	v_and_b32_e32 v0, 0xffff0000, v0
	s_waitcnt vmcnt(6)
	s_addc_u32 s9, s21, 0
	v_lshl_add_u32 v0, v13, 12, v0
	v_and_b32_e32 v1, 1, v12
	v_writelane_b32 v254, s15, 42
	s_lshl_b32 s16, s15, 1
	v_lshl_or_b32 v0, v1, 6, v0
	v_writelane_b32 v254, s16, 44
	v_ashrrev_i32_e32 v200, 4, v8
	v_mov_b32_e32 v179, v64
	v_lshl_add_u32 v180, v14, 1, v0
	v_mov_b32_e32 v181, v64
	s_mov_b32 s85, 0
	v_add_u32_e32 v202, 0, v2
	v_writelane_b32 v254, s17, 45
	s_mov_b32 s34, s72
	s_barrier
	s_branch .LBB0_322
